# g12: g8 with the attention wave-priority raise removed (checks whether static priority causes the launch-to-launch bimodality)
# speedup vs baseline: 1.0172x; 1.0172x over previous
; __device__ __forceinline__ void attn_unit(const bf16* __restrict__ proj, bf16* __restrict__ cat, int b, int h, int qb, float lam, float oscale, const float* __restrict__ subln, const float* __restrict__ cw, char* lds) {
;   int tid_ = threadIdx.x; asm volatile("" : "+v"(tid_));
;   const int tid = tid_, wid = __builtin_amdgcn_readfirstlane(tid >> 6), lane = tid & 63, r32 = lane & 31, hi = lane >> 5, rg = wid & 3, mp = wid >> 2;
;   char* K_lds = lds; char* V_lds = lds + 3 * SHM_K;
;   float* ws = (float*)(lds + OFF_WS) + wid * 64; float* li_l = ws; float* al_l = ws + 32;
;   const long rowbase = (long)b * SEQ;
;   const bf16* Kh = proj + rowbase * LDP + 1024 + h * 128; const bf16* Vh = proj + rowbase * LDP + 2048 + h * 128;
;   float m_reg = -1e30f, l_reg = 0; f32x16 o[4] = {}; bf16x8 qr[4];
;   const bf16* Qw = proj + (rowbase + qb * QROWS + rg * 32 + r32) * LDP + (2 * h + mp) * 64 + hi * 8;
.LBB0_215:
	s_mov_b64 s[28:29], -1
	s_and_b64 vcc, exec, s[20:21]
	s_cbranch_vccz .LBB0_208
	v_mov_b32_e32 v8, v161
	s_ashr_i32 s46, s73, 3
	v_readfirstlane_b32 s31, v8
	s_and_b32 s71, s31, 0xffffffc0
	s_lshl_b32 s20, s71, 2
	s_ashr_i32 s29, s31, 6
	s_add_i32 s70, s20, 0
	s_ashr_i32 s47, s46, 31
	s_and_b32 s25, s29, 3
	s_ashr_i32 s24, s31, 8
	s_cmp_lg_u32 s24, 0
	s_cbranch_scc0 .Latt_noprio
	s_setprio 0
